# prep units: idle waves of the solver stage touch the next unit's QKV rows (one dword per 128B line) so the next conv stage hits L2
# baseline (speedup 1.0000x reference)
.Lps_j:
	v_mov_b32_e32 v0, s1
	s_mov_b64 s[0:1], -1
	s_cbranch_scc0 .LBB0_550
	v_lshl_add_u32 v0, v0, 1, v147
	v_sub_u32_e32 v3, 0, v0
	v_max_i32_e32 v3, v0, v3
	v_mul_hi_u32 v4, v3, v247
	v_mul_lo_u32 v5, v4, s17
	v_sub_u32_e32 v3, v3, v5
	v_add_u32_e32 v5, 1, v4
	v_cmp_le_u32_e32 vcc, s17, v3
	v_ashrrev_i32_e32 v2, 31, v0
	v_readlane_b32 s0, v254, 33
	v_cndmask_b32_e32 v4, v4, v5, vcc
	v_subrev_u32_e32 v5, s17, v3
	v_cndmask_b32_e32 v3, v3, v5, vcc
	v_add_u32_e32 v5, 1, v4
	v_cmp_le_u32_e32 vcc, s17, v3
	v_mov_b32_e32 v148, v156
	v_bfrev_b32_e32 v165, 1
	v_cndmask_b32_e32 v3, v4, v5, vcc
	v_xor_b32_e32 v3, v3, v2
	v_sub_u32_e32 v162, v3, v2
	v_mul_lo_u32 v2, v162, s17
	v_sub_u32_e32 v161, v0, v2
	v_and_b32_e32 v164, 1, v162
	v_add_u32_e32 v2, s0, v161
	v_ashrrev_i32_e32 v0, 4, v162
	v_sub_u32_e32 v3, s36, v2
	v_cmp_eq_u32_e64 s[44:45], 0, v164
	v_readlane_b32 s0, v254, 31
	v_readlane_b32 s1, v254, 32
	v_cndmask_b32_e64 v2, v3, v2, s[44:45]
	v_lshl_add_u32 v3, v0, 8, v246
	v_lshlrev_b32_e32 v0, 12, v0
	v_cndmask_b32_e64 v26, v0, v3, s[0:1]
	v_bfe_u32 v163, v162, 1, 3
	v_ashrrev_i32_e32 v27, 31, v26
	v_lshlrev_b32_e32 v4, 6, v2
	v_mov_b32_e32 v8, 0x1fff
	v_mov_b32_e32 v9, 0x1ff
	v_cndmask_b32_e64 v8, v8, v9, s[0:1]
	v_add3_u32 v8, v4, v26, v8
	v_mad_u64_u32 v[10:11], vcc, v8, s29, 0
	v_lshlrev_b32_e32 v8, 8, v163
	v_mov_b32_e32 v9, 0
	v_lshl_add_u64 v[10:11], v[10:11], 0, v[8:9]
	v_lshl_add_u64 v[10:11], s[38:39], 0, v[10:11]
	s_nop 1
	v_readfirstlane_b32 s22, v10
	v_readfirstlane_b32 s23, v11
	v_readfirstlane_b32 vcc_lo, v4
	s_nop 3
	v_writelane_b32 v255, s22, 22
	v_writelane_b32 v255, s23, 23
	v_writelane_b32 v255, vcc_lo, 24
	v_cmp_gt_u32_e64 s[46:47], 64, v148
	v_lshl_or_b32 v130, v164, 3, v163
	v_lshlrev_b32_e32 v130, 2, v130
	s_nop 0
	v_readfirstlane_b32 s100, v130
	s_nop 4
	s_load_dword s101, s[82:83], s100
	s_load_dword s100, s[80:81], s100
	v_mov_b32_e32 v130, 0
	v_mov_b32_e32 v166, 0
	s_and_saveexec_b64 s[0:1], s[46:47]
	s_cbranch_execz .LBB0_558
	v_xor_b32_e32 v0, 63, v148
	v_ashrrev_i32_e32 v5, 31, v4
	v_cndmask_b32_e64 v0, v0, v148, s[44:45]
	v_lshl_add_u64 v[2:3], v[4:5], 0, v[26:27]
	v_or_b32_e32 v2, v2, v0
	v_readlane_b32 s22, v251, 58
	v_lshlrev_b64 v[2:3], 7, v[2:3]
	v_readlane_b32 s23, v251, 59
	v_lshlrev_b32_e32 v0, 5, v164
	s_nop 0
	v_lshl_add_u64 v[2:3], s[22:23], 0, v[2:3]
	v_lshl_add_u64 v[2:3], v[2:3], 0, v[0:1]
	v_lshlrev_b32_e32 v0, 2, v163
	v_lshl_add_u64 v[2:3], v[2:3], 0, v[0:1]
	global_load_dword v165, v[2:3], off
	global_load_dword v166, v[2:3], off offset:64

.LBB0_618:
	s_or_b64 exec, exec, s[0:1]
	v_cmp_ne_u32_e32 vcc, v51, v147
	s_cbranch_vccz .Lpfq_skip
	v_readlane_b32 s2, v250, 0
	v_readlane_b32 s22, v255, 17
	s_nop 3
	s_cmp_lt_u32 s2, 0x80
	s_cbranch_scc1 .Lpfq_skip
	s_cmp_ge_u32 s22, 3
	s_cbranch_scc1 .Lpfq_skip
	v_readlane_b32 s22, v255, 22
	v_readlane_b32 s23, v255, 23
	v_readlane_b32 s2, v255, 24
	v_mbcnt_lo_u32_b32 v2, -1, 0
	v_mbcnt_hi_u32_b32 v2, -1, v2
	v_cmp_gt_u32_e32 vcc, v51, v147
	v_cndmask_b32_e64 v3, 0, 1, vcc
	v_sub_u32_e32 v3, v51, v3
	v_lshlrev_b32_e32 v3, 11, v3
	v_add_u32_e32 v7, 1, v2
	v_mad_u32_u24 v4, v7, s29, v3
	global_load_dword v5, v4, s[22:23]
	global_load_dword v6, v4, s[22:23] offset:128
	v_mul_u32_u24_e32 v7, 0x41, v2
	v_add_u32_e32 v8, s2, v7
	v_add_u32_e32 v8, -1, v8
	v_cmp_gt_u32_e32 vcc, s16, v8
	v_cndmask_b32_e32 v7, 1, v7, vcc
	v_cmp_gt_u32_e32 vcc, 2, v2
	v_cndmask_b32_e32 v7, 1, v7, vcc
	v_mad_u32_u24 v4, v7, s29, v3
	global_load_dword v9, v4, s[22:23]
	global_load_dword v10, v4, s[22:23] offset:128
	s_waitcnt vmcnt(0)
.Lpfq_skip:
	v_lshlrev_b32_e32 v3, 5, v51
	v_or_b32_e32 v4, v3, v52
	s_movk_i32 s0, 0x48
	v_mul_lo_u32 v18, v4, s0
	v_bitop3_b32 v19, v3, 56, v52 bitop3:0xc8
	v_or_b32_e32 v20, 32, v30
	v_mul_u32_u24_e32 v3, 0x48, v52
	v_xad_u32 v20, v20, v19, v18
	v_lshlrev_b32_e32 v2, 1, v30
	v_lshlrev_b32_e32 v3, 1, v3
	v_or_b32_e32 v14, 16, v30
	v_lshl_add_u32 v90, v20, 1, v146
	v_or_b32_e32 v20, 48, v30
	v_add3_u32 v92, v146, v2, v3
	v_xad_u32 v2, v30, v19, v18
	v_xad_u32 v14, v14, v19, v18
	v_xad_u32 v18, v20, v19, v18
	s_waitcnt lgkmcnt(0)
	s_barrier
	v_lshl_add_u32 v88, v2, 1, v146
	v_lshl_add_u32 v89, v14, 1, v146
	v_lshl_add_u32 v91, v18, 1, v146
	ds_read_b128 v[2:5], v88 offset:53248
	ds_read_b128 v[6:9], v88 offset:34816
	ds_read_b128 v[10:13], v92 offset:16384
	ds_read_b128 v[34:37], v92 offset:16416
	ds_read_b128 v[38:41], v89 offset:53248
	ds_read_b128 v[42:45], v89 offset:34816
	ds_read_b128 v[14:17], v92 offset:25600
	ds_read_b128 v[52:55], v92 offset:25632
	ds_read_b128 v[56:59], v90 offset:53248
	ds_read_b128 v[60:63], v90 offset:34816
	ds_read_b128 v[64:67], v92 offset:16448
	ds_read_b128 v[68:71], v92 offset:16480
	ds_read_b128 v[72:75], v91 offset:53248
	ds_read_b128 v[76:79], v91 offset:34816
	ds_read_b128 v[80:83], v92 offset:25664
	ds_read_b128 v[84:87], v92 offset:25696
	s_mov_b64 s[0:1], 0xe000
	v_lshl_add_u64 v[48:49], v[46:47], 0, s[0:1]
	v_lshlrev_b32_e32 v96, 5, v160
	s_waitcnt lgkmcnt(13)
	v_mfma_f32_32x32x16_bf16 v[18:33], v[10:13], v[2:5], 0
	v_lshlrev_b32_e32 v51, 11, v51
	v_lshlrev_b32_e32 v97, 4, v160
	s_waitcnt lgkmcnt(9)
	v_mfma_f32_32x32x16_bf16 v[2:17], v[6:9], v[14:17], 0
	v_mfma_f32_32x32x16_bf16 v[18:33], v[34:37], v[38:41], v[18:33]
	s_waitcnt lgkmcnt(8)
	v_mfma_f32_32x32x16_bf16 v[2:17], v[42:45], v[52:55], v[2:17]
	s_waitcnt lgkmcnt(5)
	v_mfma_f32_32x32x16_bf16 v[18:33], v[64:67], v[56:59], v[18:33]
	s_waitcnt lgkmcnt(1)
	v_mfma_f32_32x32x16_bf16 v[2:17], v[60:63], v[80:83], v[2:17]
	v_mfma_f32_32x32x16_bf16 v[18:33], v[68:71], v[72:75], v[18:33]
	s_waitcnt lgkmcnt(0)
	v_mfma_f32_32x32x16_bf16 v[2:17], v[76:79], v[84:87], v[2:17]
	s_nop 9
	v_cvt_pk_bf16_f32 v18, v18, v19
	v_cvt_pk_bf16_f32 v19, v20, v21
	v_cvt_pk_bf16_f32 v20, v22, v23
	v_cvt_pk_bf16_f32 v22, v26, v27
	v_or_b32_e32 v26, v51, v96
	v_ashrrev_i32_e32 v27, 31, v26
	v_cvt_pk_bf16_f32 v21, v24, v25
	v_cvt_pk_bf16_f32 v2, v2, v3
	v_cvt_pk_bf16_f32 v3, v4, v5
	v_cvt_pk_bf16_f32 v4, v6, v7
	v_or_b32_e32 v6, v51, v97
	v_cvt_pk_bf16_f32 v23, v28, v29
	v_lshl_add_u64 v[26:27], v[48:49], 0, v[26:27]
	v_ashrrev_i32_e32 v7, 31, v6
	v_cvt_pk_bf16_f32 v24, v30, v31
	v_cvt_pk_bf16_f32 v25, v32, v33
	global_store_dwordx4 v[26:27], v[18:21], off nt
	global_store_dwordx4 v[26:27], v[22:25], off offset:16 nt
	v_cvt_pk_bf16_f32 v5, v8, v9
	s_nop 0
	v_lshl_add_u64 v[22:23], v[46:47], 0, v[6:7]
	global_store_dwordx4 v[22:23], v[2:5], off nt
	ds_read_b128 v[6:9], v88 offset:53248
	ds_read_b128 v[34:37], v88 offset:34816
	ds_read_b128 v[18:21], v92 offset:20992
	ds_read_b128 v[38:41], v92 offset:21024
	ds_read_b128 v[42:45], v89 offset:53248
	ds_read_b128 v[52:55], v89 offset:34816
	ds_read_b128 v[56:59], v92 offset:30208
	ds_read_b128 v[60:63], v92 offset:30240
	ds_read_b128 v[64:67], v90 offset:53248
	ds_read_b128 v[68:71], v90 offset:34816
	ds_read_b128 v[72:75], v92 offset:21056
	ds_read_b128 v[76:79], v92 offset:21088
	ds_read_b128 v[80:83], v91 offset:53248
	ds_read_b128 v[84:87], v91 offset:34816
	ds_read_b128 v[88:91], v92 offset:30272
	ds_read_b128 v[92:95], v92 offset:30304
	v_cvt_pk_bf16_f32 v2, v10, v11
	v_cvt_pk_bf16_f32 v3, v12, v13
	v_cvt_pk_bf16_f32 v4, v14, v15
	v_cvt_pk_bf16_f32 v5, v16, v17
	global_store_dwordx4 v[22:23], v[2:5], off offset:1024 nt
	s_waitcnt lgkmcnt(13)
	v_mfma_f32_32x32x16_bf16 v[18:33], v[18:21], v[6:9], 0
	v_cmp_eq_u32_e32 vcc, 0, v148
	s_waitcnt lgkmcnt(9)
	v_mfma_f32_32x32x16_bf16 v[2:17], v[34:37], v[56:59], 0
	v_mfma_f32_32x32x16_bf16 v[18:33], v[38:41], v[42:45], v[18:33]
	s_waitcnt lgkmcnt(8)
	v_mfma_f32_32x32x16_bf16 v[2:17], v[52:55], v[60:63], v[2:17]
	s_waitcnt lgkmcnt(5)
	v_mfma_f32_32x32x16_bf16 v[18:33], v[72:75], v[64:67], v[18:33]
	s_waitcnt lgkmcnt(1)
	v_mfma_f32_32x32x16_bf16 v[2:17], v[68:71], v[88:91], v[2:17]
	v_mfma_f32_32x32x16_bf16 v[18:33], v[76:79], v[80:83], v[18:33]
	s_waitcnt lgkmcnt(0)
	v_mfma_f32_32x32x16_bf16 v[2:17], v[84:87], v[92:95], v[2:17]
	s_nop 9
	v_cvt_pk_bf16_f32 v18, v18, v19
	v_cvt_pk_bf16_f32 v19, v20, v21
	v_cvt_pk_bf16_f32 v20, v22, v23
	v_cvt_pk_bf16_f32 v23, v28, v29
	v_add_u32_e32 v28, 0x2000, v51
	v_cvt_pk_bf16_f32 v22, v26, v27
	v_or_b32_e32 v26, v28, v96
	v_cvt_pk_bf16_f32 v2, v2, v3
	v_cvt_pk_bf16_f32 v3, v4, v5
	v_cvt_pk_bf16_f32 v4, v6, v7
	v_or_b32_e32 v6, v28, v97
	v_ashrrev_i32_e32 v27, 31, v26
	v_ashrrev_i32_e32 v7, 31, v6
	v_cvt_pk_bf16_f32 v21, v24, v25
	v_lshl_add_u64 v[26:27], v[48:49], 0, v[26:27]
	v_cvt_pk_bf16_f32 v5, v8, v9
	v_lshl_add_u64 v[6:7], v[46:47], 0, v[6:7]
	v_cvt_pk_bf16_f32 v24, v30, v31
	v_cvt_pk_bf16_f32 v25, v32, v33
	global_store_dwordx4 v[26:27], v[18:21], off nt
	global_store_dwordx4 v[26:27], v[22:25], off offset:16 nt
	global_store_dwordx4 v[6:7], v[2:5], off nt
	s_nop 1
	v_cvt_pk_bf16_f32 v2, v10, v11
	v_cvt_pk_bf16_f32 v3, v12, v13
	v_cvt_pk_bf16_f32 v4, v14, v15
	v_cvt_pk_bf16_f32 v5, v16, v17
	global_store_dwordx4 v[6:7], v[2:5], off offset:1024 nt
	s_and_saveexec_b64 s[0:1], vcc
	s_cbranch_execz .LBB0_549
	v_mul_f32_e32 v0, 0x3fb8aa3b, v0
	v_exp_f32_e32 v0, v0
	v_readlane_b32 s2, v254, 52
	v_readlane_b32 s22, v251, 60
	v_readlane_b32 s23, v251, 61
	v_add_u32_e32 v2, s2, v50
	v_ashrrev_i32_e32 v3, 31, v2
	v_lshl_add_u64 v[2:3], v[2:3], 2, s[22:23]
	global_store_dword v[2:3], v0, off
	s_branch .LBB0_549
